# attention loop: six (instead of four) PV MFMAs on pre-barrier-prefetched V fragments at the loop head
# baseline (speedup 1.0000x reference)
.LBB0_1320:
	v_readfirstlane_b32 s67, v107
	s_ashr_i32 s61, s67, 6
	s_lshl_b32 s66, s61, 4
	s_and_b32 s70, s66, 48
	v_or_b32_e32 v129, s70, v109
	v_mul_u32_u24_e32 v0, s49, v129
	s_ashr_i32 s23, s67, 8
	v_lshlrev_b32_e32 v0, 1, v0
	v_lshl_add_u64 v[2:3], s[30:31], 0, v[0:1]
	s_lshl_b32 s30, s23, 6
	s_ashr_i32 s31, s30, 31
	v_mul_lo_u32 v8, s49, v120
	v_lshl_add_u64 v[2:3], s[30:31], 1, v[2:3]
	s_lshl_b32 s31, s61, 10
	s_waitcnt vmcnt(0)
	v_mul_lo_u32 v10, s0, v122
	v_mov_b32_e32 v113, v1
	v_add_lshl_u32 v0, v8, v121, 1
	s_add_i32 s76, s2, s31
	v_lshl_add_u64 v[6:7], v[2:3], 0, v[112:113]
	v_add_lshl_u32 v8, v123, v10, 1
	v_lshl_add_u64 v[10:11], s[34:35], 0, v[0:1]
	s_mov_b32 m0, s76
	v_mul_lo_u32 v9, s0, v120
	global_load_dwordx4 v[2:5], v[6:7], off
	global_load_dwordx4 v[14:17], v[6:7], off offset:64
	s_barrier
	s_add_i32 s0, s76, 0xc000
	global_load_lds_dwordx4 v0, s[34:35]
	v_lshl_add_u64 v[10:11], v[10:11], 0, s[44:45]
	s_add_i32 m0, s76, 0x2000
	v_add_lshl_u32 v6, v9, v121, 1
	global_load_lds_dwordx4 v[10:11], off
	s_mov_b32 m0, s0
	s_add_i32 s0, s59, s31
	global_load_lds_dwordx4 v6, s[36:37]
	s_add_i32 m0, s76, 0xe000
	s_lshl_b32 s74, s49, 7
	global_load_lds_dwordx4 v8, s[36:37]
	s_add_i32 m0, s76, 0x4000
	s_add_u32 s50, s34, s74
	s_addc_u32 s51, s35, 0
	v_mov_b32_e32 v7, v1
	s_waitcnt vmcnt(0)
	v_lshl_add_u64 v[18:19], s[50:51], 0, v[0:1]
	v_lshl_add_u64 v[10:11], s[36:37], 0, v[6:7]
	v_mov_b32_e32 v9, v1
	global_load_lds_dwordx4 v0, s[50:51]
	v_lshl_add_u64 v[18:19], v[18:19], 0, s[44:45]
	s_add_i32 m0, s76, 0x6000
	v_lshl_add_u64 v[12:13], s[36:37], 0, v[8:9]
	global_load_lds_dwordx4 v[18:19], off
	v_lshl_add_u64 v[18:19], v[10:11], 0, s[44:45]
	s_mov_b32 m0, s0
	s_mov_b32 s77, 1
	global_load_lds_dwordx4 v[18:19], off
	v_lshl_add_u64 v[18:19], v[12:13], 0, s[44:45]
	s_add_i32 m0, s0, 0x2000
	s_add_i32 s0, s60, s31
	global_load_lds_dwordx4 v[18:19], off
	s_add_i32 m0, s76, 0x8000
	s_add_u32 s50, s50, s74
	s_addc_u32 s51, s51, 0
	v_lshl_add_u64 v[18:19], s[50:51], 0, v[0:1]
	global_load_lds_dwordx4 v0, s[50:51]
	v_lshl_add_u64 v[18:19], v[18:19], 0, s[44:45]
	s_add_i32 m0, s76, 0xa000
	s_mov_b64 s[50:51], 0x100
	global_load_lds_dwordx4 v[18:19], off
	v_lshl_add_u64 v[10:11], v[10:11], 0, s[50:51]
	s_mov_b32 m0, s0
	s_nop 0
	global_load_lds_dwordx4 v[10:11], off
	v_lshl_add_u64 v[10:11], v[12:13], 0, s[50:51]
	s_add_i32 m0, s0, 0x2000
	s_nop 0
	global_load_lds_dwordx4 v[10:11], off
	v_lshlrev_b32_e32 v10, 16, v2
	v_and_b32_e32 v11, 0xffff0000, v2
	s_mov_b32 s0, 0x3e38aa3b
	v_lshlrev_b32_e32 v2, 16, v3
	v_and_b32_e32 v3, 0xffff0000, v3
	v_pk_mul_f32 v[10:11], v[10:11], s[0:1] op_sel_hi:[1,0]
	v_pk_mul_f32 v[2:3], v[2:3], s[0:1] op_sel_hi:[1,0]
	v_cvt_pk_bf16_f32 v10, v10, v11
	v_cvt_pk_bf16_f32 v11, v2, v3
	v_lshlrev_b32_e32 v2, 16, v4
	v_and_b32_e32 v3, 0xffff0000, v4
	v_pk_mul_f32 v[2:3], v[2:3], s[0:1] op_sel_hi:[1,0]
	s_lshl_b32 s50, s23, 13
	v_cvt_pk_bf16_f32 v12, v2, v3
	v_lshlrev_b32_e32 v2, 16, v5
	v_and_b32_e32 v3, 0xffff0000, v5
	v_pk_mul_f32 v[2:3], v[2:3], s[0:1] op_sel_hi:[1,0]
	s_waitcnt vmcnt(8)
	s_barrier
	v_cvt_pk_bf16_f32 v13, v2, v3
	v_lshlrev_b32_e32 v2, 16, v14
	v_and_b32_e32 v3, 0xffff0000, v14
	v_pk_mul_f32 v[2:3], v[2:3], s[0:1] op_sel_hi:[1,0]
	v_add_u32_e32 v34, s50, v124
	v_cvt_pk_bf16_f32 v18, v2, v3
	v_lshlrev_b32_e32 v2, 16, v15
	v_and_b32_e32 v3, 0xffff0000, v15
	v_pk_mul_f32 v[14:15], v[2:3], s[0:1] op_sel_hi:[1,0]
	ds_read_b128 v[2:5], v34
	ds_read_b128 v[22:25], v34 offset:1024
	v_cvt_pk_bf16_f32 v19, v14, v15
	v_lshlrev_b32_e32 v14, 16, v16
	v_and_b32_e32 v15, 0xffff0000, v16
	v_pk_mul_f32 v[14:15], v[14:15], s[0:1] op_sel_hi:[1,0]
	v_lshlrev_b32_e32 v26, 16, v17
	v_cvt_pk_bf16_f32 v20, v14, v15
	v_and_b32_e32 v27, 0xffff0000, v17
	s_waitcnt lgkmcnt(0)
	v_mfma_f32_16x16x32_bf16 v[2:5], v[2:5], v[10:13], 0
	ds_read_b128 v[14:17], v34 offset:2048
	v_pk_mul_f32 v[26:27], v[26:27], s[0:1] op_sel_hi:[1,0]
	ds_read_b128 v[30:33], v34 offset:6144
	v_cvt_pk_bf16_f32 v21, v26, v27
	ds_read_b128 v[26:29], v34 offset:4096
	s_waitcnt lgkmcnt(0)
	v_mfma_f32_16x16x32_bf16 v[30:33], v[30:33], v[10:13], 0
	s_add_i32 s0, s71, -2
	s_mulk_i32 s49, 0x180
	s_add_u32 s34, s34, s49
	v_mfma_f32_16x16x32_bf16 v[22:25], v[22:25], v[18:21], v[2:5]
	s_addc_u32 s35, s35, 0
	v_lshl_add_u64 v[114:115], s[34:35], 0, v[0:1]
	s_add_u32 s34, s36, 0x180
	ds_read_b128 v[2:5], v34 offset:3072
	v_mfma_f32_16x16x32_bf16 v[14:17], v[14:17], v[10:13], 0
	s_mov_b32 s88, s75
	s_mov_b32 s89, s75
	s_addc_u32 s35, s37, 0
	s_waitcnt lgkmcnt(0)
	v_mfma_f32_16x16x32_bf16 v[14:17], v[2:5], v[18:21], v[14:17]
	ds_read_b128 v[2:5], v34 offset:5120
	ds_read_b128 v[34:37], v34 offset:7168
	s_mov_b32 s90, s75
	v_mfma_f32_16x16x32_bf16 v[26:29], v[26:29], v[10:13], 0
	s_mov_b32 s91, s75
	v_lshl_add_u64 v[118:119], s[34:35], 0, v[6:7]
	v_mov_b32_e32 v6, 0
	s_waitcnt lgkmcnt(0)
	v_mfma_f32_16x16x32_bf16 v[26:29], v[2:5], v[18:21], v[26:29]
	v_mov_b64_e32 v[2:3], s[88:89]
	v_mov_b64_e32 v[4:5], s[90:91]
	v_lshl_add_u64 v[116:117], s[34:35], 0, v[8:9]
	v_mfma_f32_16x16x32_bf16 v[30:33], v[34:37], v[18:21], v[30:33]
	v_max_f32_e32 v34, v25, v25
	v_max_f32_e32 v35, v24, v24
	v_max_f32_e32 v34, v35, v34
	v_max_f32_e32 v35, v17, v17
	v_max_f32_e32 v36, v16, v16
	v_max_f32_e32 v35, v36, v35
	v_max_f32_e32 v36, v27, v27
	v_max_f32_e32 v37, v26, v26
	v_max_f32_e32 v36, v37, v36
	v_max_f32_e32 v37, v29, v29
	v_max_f32_e32 v38, v28, v28
	v_max_f32_e32 v37, v38, v37
	v_max_f32_e32 v38, v33, v33
	v_max_f32_e32 v39, v32, v32
	v_max_f32_e32 v38, v39, v38
	v_max3_f32 v38, v30, v31, v38
	v_max3_f32 v34, v22, v23, v34
	v_max3_f32 v35, v14, v15, v35
	v_max3_f32 v36, v36, v37, v38
	v_max3_f32 v34, v34, v35, v36
	v_mov_b32_e32 v35, v34
	s_nop 1
	v_permlane16_swap_b32_e32 v34, v35
	v_max_f32_e32 v35, v35, v35
	v_max_f32_e32 v34, v34, v34
	v_max_f32_e32 v34, v34, v35
	v_mov_b32_e32 v35, v34
	s_nop 1
	v_permlane32_swap_b32_e32 v34, v35
	v_max_f32_e32 v35, v35, v35
	v_max_f32_e32 v34, v34, v34
	v_max_f32_e32 v113, v34, v35
	v_sub_f32_e32 v74, v22, v113
	v_sub_f32_e32 v22, v26, v113
	v_sub_f32_e32 v26, v30, v113
	v_mov_b32_e32 v30, 0
	v_sub_f32_e32 v77, v25, v113
	v_sub_f32_e32 v76, v24, v113
	v_sub_f32_e32 v75, v23, v113
	v_sub_f32_e32 v73, v17, v113
	v_sub_f32_e32 v72, v16, v113
	v_sub_f32_e32 v71, v15, v113
	v_sub_f32_e32 v70, v14, v113
	v_sub_f32_e32 v25, v29, v113
	v_sub_f32_e32 v24, v28, v113
	v_sub_f32_e32 v23, v27, v113
	v_sub_f32_e32 v29, v33, v113
	v_sub_f32_e32 v28, v32, v113
	v_sub_f32_e32 v27, v31, v113
	v_add_u32_e32 v130, s50, v127
	s_mov_b32 s36, 0
	s_mov_b32 s37, 3
	s_mov_b32 s49, 0
	s_mov_b32 s72, 0
	s_mov_b32 s50, 0
	v_mov_b32_e32 v7, v6
	v_mov_b32_e32 v8, v6
	v_mov_b32_e32 v9, v6
	v_mov_b32_e32 v14, v6
	v_mov_b32_e32 v15, v6
	v_mov_b32_e32 v16, v6
	v_mov_b32_e32 v17, v6
	v_mov_b32_e32 v31, v30
	v_mov_b32_e32 v32, v30
	v_mov_b32_e32 v33, v30
	v_mov_b32_e32 v50, v30
	v_mov_b32_e32 v51, v30
	v_mov_b32_e32 v52, v30
	v_mov_b32_e32 v53, v30
	v_mov_b32_e32 v42, v30
	v_mov_b32_e32 v43, v30
	v_mov_b32_e32 v44, v30
	v_mov_b32_e32 v45, v30
	v_mov_b32_e32 v34, v30
	v_mov_b32_e32 v35, v30
	v_mov_b32_e32 v36, v30
	v_mov_b32_e32 v37, v30
	v_mov_b32_e32 v58, v30
	v_mov_b32_e32 v59, v30
	v_mov_b32_e32 v60, v30
	v_mov_b32_e32 v61, v30
	v_mov_b32_e32 v54, v30
	v_mov_b32_e32 v55, v30
	v_mov_b32_e32 v56, v30
	v_mov_b32_e32 v57, v30
	v_mov_b32_e32 v46, v30
	v_mov_b32_e32 v47, v30
	v_mov_b32_e32 v48, v30
	v_mov_b32_e32 v49, v30
	v_mov_b32_e32 v38, v30
	v_mov_b32_e32 v39, v30
	v_mov_b32_e32 v40, v30
	v_mov_b32_e32 v41, v30
	v_mov_b32_e32 v194, 0
	v_xor_b32_e32 v150, 0x80000000, v113
	v_mov_b32_e32 v154, s48
	v_mov_b32_e32 v151, v150
	v_mov_b32_e32 v155, v154
	v_mov_b32_e32 v152, v150
	v_mov_b32_e32 v156, v154
	v_mov_b32_e32 v153, v150
	v_mov_b32_e32 v157, v154
	s_lshl_b32 s51, s49, 14
	v_add_u32_e32 v131, s51, v124
	ds_read_b128 v[204:207], v131 offset:49152
	ds_read_b128 v[208:211], v131 offset:51200
	ds_read_b128 v[212:215], v131 offset:53248
	ds_read_b128 v[216:219], v131 offset:55296
	ds_read_b128 v[220:223], v131 offset:57344
	ds_read_b128 v[140:143], v131 offset:59392
	s_mov_b64 s[88:89], s[86:87]
	s_cmp_ge_u32 s50, s0
	s_mov_b64 s[34:35], -1
	s_cbranch_scc0 .LBB0_1322

.LBB0_1326:
	s_mul_hi_u32 s34, s77, 0xaaaaaaab
	s_lshr_b32 s34, s34, 1
	s_mul_i32 s34, s34, 0xc000
	v_subrev_u32_e32 v0, s34, v130
	s_add_i32 s34, s2, s36
	v_add_u32_e32 v0, s34, v0
	ds_read_b128 v[188:191], v0
	ds_read_b128 v[82:85], v0 offset:4096
	ds_read_b128 v[94:97], v0 offset:6144
	ds_read_b128 v[98:101], v0 offset:1024
	ds_read_b128 v[86:89], v0 offset:2048
	ds_read_b128 v[132:135], v0 offset:3072
	s_waitcnt lgkmcnt(11)
	v_mfma_f32_16x16x32_bf16 v[30:33], v[204:207], v[14:17], v[30:33]
	s_waitcnt lgkmcnt(10)
	v_mfma_f32_16x16x32_bf16 v[50:53], v[208:211], v[14:17], v[50:53]
	s_waitcnt lgkmcnt(9)
	v_mfma_f32_16x16x32_bf16 v[42:45], v[212:215], v[14:17], v[42:45]
	s_waitcnt lgkmcnt(8)
	v_mfma_f32_16x16x32_bf16 v[34:37], v[216:219], v[14:17], v[34:37]
	s_waitcnt lgkmcnt(7)
	v_mfma_f32_16x16x32_bf16 v[58:61], v[220:223], v[14:17], v[58:61]
	s_waitcnt lgkmcnt(6)
	v_mfma_f32_16x16x32_bf16 v[54:57], v[140:143], v[14:17], v[54:57]
	s_waitcnt lgkmcnt(5)
	v_mfma_f32_16x16x32_bf16 v[188:191], v[188:191], v[10:13], v[150:153]
	ds_read_b128 v[78:81], v0 offset:5120
	s_waitcnt lgkmcnt(2)
	v_mfma_f32_16x16x32_bf16 v[136:139], v[86:89], v[10:13], v[150:153]
	ds_read_b128 v[86:89], v0 offset:7168
	v_mfma_f32_16x16x32_bf16 v[90:93], v[82:85], v[10:13], v[150:153]
	v_mfma_f32_16x16x32_bf16 v[94:97], v[94:97], v[10:13], v[150:153]
	v_mfma_f32_16x16x32_bf16 v[160:163], v[98:101], v[18:21], v[188:191]
	s_waitcnt lgkmcnt(2)
	v_mfma_f32_16x16x32_bf16 v[164:167], v[132:135], v[18:21], v[136:139]
	s_mov_b32 s34, 0x41000000
	v_cmp_lt_f32_e32 vcc, s34, v194
	s_cmp_lg_u64 vcc, 0
	s_cselect_b64 s[34:35], -1, 0
	s_cbranch_vccz .LBB0_1328
	v_cndmask_b32_e32 v132, 0, v194, vcc
	v_exp_f32_e64 v0, -v132
	v_sub_f32_e32 v74, v74, v132
	v_sub_f32_e32 v75, v75, v132
	v_sub_f32_e32 v76, v76, v132
	v_sub_f32_e32 v77, v77, v132
	v_sub_f32_e32 v70, v70, v132
	v_sub_f32_e32 v71, v71, v132
	v_sub_f32_e32 v72, v72, v132
	v_sub_f32_e32 v73, v73, v132
	v_sub_f32_e32 v22, v22, v132
	v_sub_f32_e32 v23, v23, v132
	v_sub_f32_e32 v24, v24, v132
	v_sub_f32_e32 v25, v25, v132
	v_sub_f32_e32 v26, v26, v132
	v_sub_f32_e32 v27, v27, v132
	v_sub_f32_e32 v28, v28, v132
	v_sub_f32_e32 v29, v29, v132
	v_add_f32_e32 v113, v113, v132
	v_xor_b32_e32 v150, 0x80000000, v113
	v_mov_b32_e32 v151, v150
	v_mov_b32_e32 v152, v150
	v_mov_b32_e32 v153, v150
	s_branch .LBB0_1329
.LBB0_1328:
.LBB0_1329:
	s_waitcnt lgkmcnt(1)
	v_mfma_f32_16x16x32_bf16 v[168:171], v[78:81], v[18:21], v[90:93]
	ds_read_b128 v[176:179], v131 offset:61440
	s_waitcnt lgkmcnt(1)
	v_mfma_f32_16x16x32_bf16 v[172:175], v[86:89], v[18:21], v[94:97]
	ds_read_b128 v[82:85], v131 offset:63488
	v_exp_f32_e32 v145, v74
	v_exp_f32_e32 v146, v75
	v_exp_f32_e32 v147, v76
	v_exp_f32_e32 v148, v77
	ds_read_b128 v[90:93], v131 offset:50176
	ds_read_b128 v[78:81], v131 offset:54272
	v_max3_f32 v195, v160, v161, v162
	v_max3_f32 v195, v195, v163, v164
	v_max3_f32 v195, v195, v165, v166
	v_max_f32_e32 v195, v195, v167
	s_waitcnt lgkmcnt(3)
	v_mfma_f32_16x16x32_bf16 v[46:49], v[176:179], v[14:17], v[46:49]
	ds_read_b128 v[176:179], v131 offset:58368
	ds_read_b128 v[86:89], v131 offset:56320
	s_cmp_ge_u32 s73, s71
	s_cbranch_scc1 .Latt_stgA_skip
	s_mul_hi_u32 s49, s50, 0xaaaaaaab
	s_lshr_b32 s49, s49, 1
	s_mul_i32 s49, s49, 0xc000
	s_sub_i32 s49, s31, s49
	s_add_i32 s49, s36, s49
	s_add_i32 s49, s2, s49
	s_lshl_b32 s51, s37, 14
	s_add_i32 s51, s76, s51
	s_mov_b32 m0, s49
	s_add_i32 s50, s51, 0xc000
	global_load_lds_dwordx4 v[114:115], off
	v_lshl_add_u64 v[192:193], v[114:115], 0, s[44:45]
	s_add_i32 m0, s49, 0x2000
	s_nop 0
	global_load_lds_dwordx4 v[192:193], off
	s_mov_b32 m0, s50
	s_nop 0
	global_load_lds_dwordx4 v[118:119], off
	s_add_i32 m0, s51, 0xe000
	s_nop 0
	global_load_lds_dwordx4 v[116:117], off
.Latt_stgA_skip:
	ds_read_b128 v[180:183], v131 offset:52224
	s_waitcnt lgkmcnt(5)
	v_mfma_f32_16x16x32_bf16 v[38:41], v[82:85], v[14:17], v[38:41]
	v_exp_f32_e32 v98, v70
	v_exp_f32_e32 v99, v71
	v_exp_f32_e32 v100, v72
	v_exp_f32_e32 v101, v73
	v_max3_f32 v194, v168, v169, v170
	v_max3_f32 v194, v194, v171, v172
	v_max3_f32 v194, v194, v173, v174
	v_max3_f32 v194, v194, v175, v195
	v_mfma_f32_16x16x32_bf16 v[2:5], v[154:157], v[14:17], v[2:5]
	v_exp_f32_e32 v102, v22
	v_exp_f32_e32 v103, v23
	v_exp_f32_e32 v104, v24
	v_exp_f32_e32 v105, v25
	ds_read_b128 v[94:97], v131 offset:60416
	s_waitcnt lgkmcnt(5)
	v_mfma_f32_16x16x32_bf16 v[30:33], v[90:93], v[6:9], v[30:33]
	ds_read_b128 v[90:93], v131 offset:62464
	v_mov_b32_e32 v158, v194
	s_nop 1
	v_permlane16_swap_b32_e32 v194, v158
	v_max_f32_e32 v194, v194, v158
	s_waitcnt lgkmcnt(2)
	v_mfma_f32_16x16x32_bf16 v[50:53], v[180:183], v[6:9], v[50:53]
	ds_read_b128 v[180:183], v131 offset:64512
	v_exp_f32_e32 v133, v26
	v_exp_f32_e32 v134, v27
	v_exp_f32_e32 v135, v28
	v_exp_f32_e32 v136, v29
	v_mfma_f32_16x16x32_bf16 v[42:45], v[78:81], v[6:9], v[42:45]
	v_mov_b32_e32 v158, v194
	s_nop 1
	v_permlane32_swap_b32_e32 v194, v158
	v_max_f32_e32 v194, v194, v158
	v_mfma_f32_16x16x32_bf16 v[34:37], v[86:89], v[6:9], v[34:37]
	v_cvt_pk_bf16_f32 v14, v145, v146
	v_cvt_pk_bf16_f32 v15, v147, v148
	v_cvt_pk_bf16_f32 v16, v98, v99
	v_cvt_pk_bf16_f32 v17, v100, v101
	v_cvt_pk_bf16_f32 v184, v102, v103
	v_cvt_pk_bf16_f32 v185, v104, v105
	v_cvt_pk_bf16_f32 v186, v133, v134
	v_cvt_pk_bf16_f32 v187, v135, v136
	v_mfma_f32_16x16x32_bf16 v[58:61], v[176:179], v[6:9], v[58:61]
	s_waitcnt lgkmcnt(2)
	v_mfma_f32_16x16x32_bf16 v[54:57], v[94:97], v[6:9], v[54:57]
	s_waitcnt lgkmcnt(1)
	v_mfma_f32_16x16x32_bf16 v[46:49], v[90:93], v[6:9], v[46:49]
	s_waitcnt lgkmcnt(0)
	v_mfma_f32_16x16x32_bf16 v[38:41], v[180:183], v[6:9], v[38:41]
	v_mfma_f32_16x16x32_bf16 v[2:5], v[154:157], v[6:9], v[2:5]
	s_andn2_b64 vcc, exec, s[34:35]
	s_cbranch_vccnz .LBB0_1331
	v_sub_f32_e32 v160, v160, v132
	v_sub_f32_e32 v161, v161, v132
	v_sub_f32_e32 v162, v162, v132
	v_sub_f32_e32 v163, v163, v132
	v_sub_f32_e32 v164, v164, v132
	v_sub_f32_e32 v165, v165, v132
	v_sub_f32_e32 v166, v166, v132
	v_sub_f32_e32 v167, v167, v132
	v_sub_f32_e32 v168, v168, v132
	v_sub_f32_e32 v169, v169, v132
	v_sub_f32_e32 v170, v170, v132
	v_sub_f32_e32 v171, v171, v132
	v_sub_f32_e32 v172, v172, v132
	v_sub_f32_e32 v173, v173, v132
	v_sub_f32_e32 v174, v174, v132
	v_sub_f32_e32 v175, v175, v132
	v_sub_f32_e32 v194, v194, v132
	v_pk_mul_f32 v[40:41], v[0:1], v[40:41] op_sel_hi:[0,1]
	v_pk_mul_f32 v[48:49], v[0:1], v[48:49] op_sel_hi:[0,1]
	v_pk_mul_f32 v[56:57], v[0:1], v[56:57] op_sel_hi:[0,1]
	v_pk_mul_f32 v[60:61], v[0:1], v[60:61] op_sel_hi:[0,1]
	v_pk_mul_f32 v[36:37], v[0:1], v[36:37] op_sel_hi:[0,1]
	v_pk_mul_f32 v[44:45], v[0:1], v[44:45] op_sel_hi:[0,1]
	v_pk_mul_f32 v[52:53], v[0:1], v[52:53] op_sel_hi:[0,1]
	v_pk_mul_f32 v[32:33], v[0:1], v[32:33] op_sel_hi:[0,1]
	v_pk_mul_f32 v[38:39], v[0:1], v[38:39] op_sel_hi:[0,1]
	v_pk_mul_f32 v[46:47], v[0:1], v[46:47] op_sel_hi:[0,1]
	v_pk_mul_f32 v[54:55], v[0:1], v[54:55] op_sel_hi:[0,1]
	v_pk_mul_f32 v[58:59], v[0:1], v[58:59] op_sel_hi:[0,1]
	v_pk_mul_f32 v[34:35], v[0:1], v[34:35] op_sel_hi:[0,1]
	v_pk_mul_f32 v[42:43], v[0:1], v[42:43] op_sel_hi:[0,1]
	v_pk_mul_f32 v[50:51], v[0:1], v[50:51] op_sel_hi:[0,1]
	v_pk_mul_f32 v[30:31], v[0:1], v[30:31] op_sel_hi:[0,1]
	v_pk_mul_f32 v[4:5], v[0:1], v[4:5] op_sel_hi:[0,1]
	v_pk_mul_f32 v[2:3], v[0:1], v[2:3] op_sel_hi:[0,1]
.LBB0_1331:
	s_add_i32 s34, s72, 1
	s_cmp_lg_u32 s72, 4
	s_cselect_b32 s34, s34, 0
	s_add_i32 s35, s37, 1
	s_cmp_lg_u32 s37, 4
	s_cselect_b32 s37, s35, 0
	s_addk_i32 s36, 0x4000
	s_add_i32 s77, s77, 1
	s_add_i32 s50, s73, -2
	v_lshl_add_u64 v[114:115], v[114:115], 0, s[74:75]
	v_lshl_add_u64 v[116:117], v[116:117], 0, s[44:45]
	s_cmp_eq_u32 s50, s71
	v_lshl_add_u64 v[118:119], v[118:119], 0, s[44:45]
	s_cbranch_scc1 .Latt_exitA
	s_mov_b32 s49, s72
	s_lshl_b32 s51, s49, 14
	v_add_u32_e32 v131, s51, v124
	ds_read_b128 v[204:207], v131 offset:49152
	ds_read_b128 v[208:211], v131 offset:51200
	ds_read_b128 v[212:215], v131 offset:53248
	ds_read_b128 v[216:219], v131 offset:55296
	ds_read_b128 v[220:223], v131 offset:57344
	ds_read_b128 v[140:143], v131 offset:59392
	s_mov_b32 s72, s34
	s_cmp_ge_u32 s50, s0
	s_mov_b64 s[34:35], -1
	s_cbranch_scc1 .Latt_B_1321
	s_branch .Latt_B_1322

.Latt_B_1326:
	s_mul_hi_u32 s34, s77, 0xaaaaaaab
	s_lshr_b32 s34, s34, 1
	s_mul_i32 s34, s34, 0xc000
	v_subrev_u32_e32 v0, s34, v130
	s_add_i32 s34, s2, s36
	v_add_u32_e32 v0, s34, v0
	ds_read_b128 v[188:191], v0
	ds_read_b128 v[82:85], v0 offset:4096
	ds_read_b128 v[94:97], v0 offset:6144
	ds_read_b128 v[98:101], v0 offset:1024
	ds_read_b128 v[86:89], v0 offset:2048
	ds_read_b128 v[132:135], v0 offset:3072
	s_waitcnt lgkmcnt(11)
	v_mfma_f32_16x16x32_bf16 v[30:33], v[204:207], v[14:17], v[30:33]
	s_waitcnt lgkmcnt(10)
	v_mfma_f32_16x16x32_bf16 v[50:53], v[208:211], v[14:17], v[50:53]
	s_waitcnt lgkmcnt(9)
	v_mfma_f32_16x16x32_bf16 v[42:45], v[212:215], v[14:17], v[42:45]
	s_waitcnt lgkmcnt(8)
	v_mfma_f32_16x16x32_bf16 v[34:37], v[216:219], v[14:17], v[34:37]
	s_waitcnt lgkmcnt(7)
	v_mfma_f32_16x16x32_bf16 v[58:61], v[220:223], v[14:17], v[58:61]
	s_waitcnt lgkmcnt(6)
	v_mfma_f32_16x16x32_bf16 v[54:57], v[140:143], v[14:17], v[54:57]
	s_waitcnt lgkmcnt(5)
	v_mfma_f32_16x16x32_bf16 v[188:191], v[188:191], v[10:13], v[150:153]
	ds_read_b128 v[78:81], v0 offset:5120
	s_waitcnt lgkmcnt(2)
	v_mfma_f32_16x16x32_bf16 v[136:139], v[86:89], v[10:13], v[150:153]
	ds_read_b128 v[86:89], v0 offset:7168
	v_mfma_f32_16x16x32_bf16 v[90:93], v[82:85], v[10:13], v[150:153]
	v_mfma_f32_16x16x32_bf16 v[94:97], v[94:97], v[10:13], v[150:153]
	v_mfma_f32_16x16x32_bf16 v[74:77], v[98:101], v[18:21], v[188:191]
	s_waitcnt lgkmcnt(2)
	v_mfma_f32_16x16x32_bf16 v[70:73], v[132:135], v[18:21], v[136:139]
	s_mov_b32 s34, 0x41000000
	v_cmp_lt_f32_e32 vcc, s34, v194
	s_cmp_lg_u64 vcc, 0
	s_cselect_b64 s[34:35], -1, 0
	s_cbranch_vccz .Latt_B_1328
	v_cndmask_b32_e32 v132, 0, v194, vcc
	v_exp_f32_e64 v0, -v132
	v_sub_f32_e32 v160, v160, v132
	v_sub_f32_e32 v161, v161, v132
	v_sub_f32_e32 v162, v162, v132
	v_sub_f32_e32 v163, v163, v132
	v_sub_f32_e32 v164, v164, v132
	v_sub_f32_e32 v165, v165, v132
	v_sub_f32_e32 v166, v166, v132
	v_sub_f32_e32 v167, v167, v132
	v_sub_f32_e32 v168, v168, v132
	v_sub_f32_e32 v169, v169, v132
	v_sub_f32_e32 v170, v170, v132
	v_sub_f32_e32 v171, v171, v132
	v_sub_f32_e32 v172, v172, v132
	v_sub_f32_e32 v173, v173, v132
	v_sub_f32_e32 v174, v174, v132
	v_sub_f32_e32 v175, v175, v132
	v_add_f32_e32 v113, v113, v132
	v_xor_b32_e32 v150, 0x80000000, v113
	v_mov_b32_e32 v151, v150
	v_mov_b32_e32 v152, v150
	v_mov_b32_e32 v153, v150
	s_branch .Latt_B_1329
.Latt_B_1328:
.Latt_B_1329:
	s_waitcnt lgkmcnt(1)
	v_mfma_f32_16x16x32_bf16 v[22:25], v[78:81], v[18:21], v[90:93]
	ds_read_b128 v[176:179], v131 offset:61440
	s_waitcnt lgkmcnt(1)
	v_mfma_f32_16x16x32_bf16 v[26:29], v[86:89], v[18:21], v[94:97]
	ds_read_b128 v[82:85], v131 offset:63488
	v_exp_f32_e32 v145, v160
	v_exp_f32_e32 v146, v161
	v_exp_f32_e32 v147, v162
	v_exp_f32_e32 v148, v163
	ds_read_b128 v[90:93], v131 offset:50176
	ds_read_b128 v[78:81], v131 offset:54272
	v_max3_f32 v195, v74, v75, v76
	v_max3_f32 v195, v195, v77, v70
	v_max3_f32 v195, v195, v71, v72
	v_max_f32_e32 v195, v195, v73
	s_waitcnt lgkmcnt(3)
	v_mfma_f32_16x16x32_bf16 v[46:49], v[176:179], v[14:17], v[46:49]
	ds_read_b128 v[176:179], v131 offset:58368
	ds_read_b128 v[86:89], v131 offset:56320
	s_cmp_ge_u32 s73, s71
	s_cbranch_scc1 .Latt_stgB_skip
	s_mul_hi_u32 s49, s50, 0xaaaaaaab
	s_lshr_b32 s49, s49, 1
	s_mul_i32 s49, s49, 0xc000
	s_sub_i32 s49, s31, s49
	s_add_i32 s49, s36, s49
	s_add_i32 s49, s2, s49
	s_lshl_b32 s51, s37, 14
	s_add_i32 s51, s76, s51
	s_mov_b32 m0, s49
	s_add_i32 s50, s51, 0xc000
	global_load_lds_dwordx4 v[114:115], off
	v_lshl_add_u64 v[192:193], v[114:115], 0, s[44:45]
	s_add_i32 m0, s49, 0x2000
	s_nop 0
	global_load_lds_dwordx4 v[192:193], off
	s_mov_b32 m0, s50
	s_nop 0
	global_load_lds_dwordx4 v[118:119], off
	s_add_i32 m0, s51, 0xe000
	s_nop 0
	global_load_lds_dwordx4 v[116:117], off
.Latt_stgB_skip:
	ds_read_b128 v[180:183], v131 offset:52224
	s_waitcnt lgkmcnt(5)
	v_mfma_f32_16x16x32_bf16 v[38:41], v[82:85], v[14:17], v[38:41]
	v_exp_f32_e32 v98, v164
	v_exp_f32_e32 v99, v165
	v_exp_f32_e32 v100, v166
	v_exp_f32_e32 v101, v167
	v_max3_f32 v194, v22, v23, v24
	v_max3_f32 v194, v194, v25, v26
	v_max3_f32 v194, v194, v27, v28
	v_max3_f32 v194, v194, v29, v195
	v_mfma_f32_16x16x32_bf16 v[2:5], v[154:157], v[14:17], v[2:5]
	v_exp_f32_e32 v102, v168
	v_exp_f32_e32 v103, v169
	v_exp_f32_e32 v104, v170
	v_exp_f32_e32 v105, v171
	ds_read_b128 v[94:97], v131 offset:60416
	s_waitcnt lgkmcnt(5)
	v_mfma_f32_16x16x32_bf16 v[30:33], v[90:93], v[184:187], v[30:33]
	ds_read_b128 v[90:93], v131 offset:62464
	v_mov_b32_e32 v158, v194
	s_nop 1
	v_permlane16_swap_b32_e32 v194, v158
	v_max_f32_e32 v194, v194, v158
	s_waitcnt lgkmcnt(2)
	v_mfma_f32_16x16x32_bf16 v[50:53], v[180:183], v[184:187], v[50:53]
	ds_read_b128 v[180:183], v131 offset:64512
	v_exp_f32_e32 v133, v172
	v_exp_f32_e32 v134, v173
	v_exp_f32_e32 v135, v174
	v_exp_f32_e32 v136, v175
	v_mfma_f32_16x16x32_bf16 v[42:45], v[78:81], v[184:187], v[42:45]
	v_mov_b32_e32 v158, v194
	s_nop 1
	v_permlane32_swap_b32_e32 v194, v158
	v_max_f32_e32 v194, v194, v158
	v_mfma_f32_16x16x32_bf16 v[34:37], v[86:89], v[184:187], v[34:37]
	v_cvt_pk_bf16_f32 v14, v145, v146
	v_cvt_pk_bf16_f32 v15, v147, v148
	v_cvt_pk_bf16_f32 v16, v98, v99
	v_cvt_pk_bf16_f32 v17, v100, v101
	v_cvt_pk_bf16_f32 v6, v102, v103
	v_cvt_pk_bf16_f32 v7, v104, v105
	v_cvt_pk_bf16_f32 v8, v133, v134
	v_cvt_pk_bf16_f32 v9, v135, v136
	v_mfma_f32_16x16x32_bf16 v[58:61], v[176:179], v[184:187], v[58:61]
	s_waitcnt lgkmcnt(2)
	v_mfma_f32_16x16x32_bf16 v[54:57], v[94:97], v[184:187], v[54:57]
	s_waitcnt lgkmcnt(1)
	v_mfma_f32_16x16x32_bf16 v[46:49], v[90:93], v[184:187], v[46:49]
	s_waitcnt lgkmcnt(0)
	v_mfma_f32_16x16x32_bf16 v[38:41], v[180:183], v[184:187], v[38:41]
	v_mfma_f32_16x16x32_bf16 v[2:5], v[154:157], v[184:187], v[2:5]
	s_andn2_b64 vcc, exec, s[34:35]
	s_cbranch_vccnz .Latt_B_1331
	v_sub_f32_e32 v74, v74, v132
	v_sub_f32_e32 v75, v75, v132
	v_sub_f32_e32 v76, v76, v132
	v_sub_f32_e32 v77, v77, v132
	v_sub_f32_e32 v70, v70, v132
	v_sub_f32_e32 v71, v71, v132
	v_sub_f32_e32 v72, v72, v132
	v_sub_f32_e32 v73, v73, v132
	v_sub_f32_e32 v22, v22, v132
	v_sub_f32_e32 v23, v23, v132
	v_sub_f32_e32 v24, v24, v132
	v_sub_f32_e32 v25, v25, v132
	v_sub_f32_e32 v26, v26, v132
	v_sub_f32_e32 v27, v27, v132
	v_sub_f32_e32 v28, v28, v132
	v_sub_f32_e32 v29, v29, v132
	v_sub_f32_e32 v194, v194, v132
	v_pk_mul_f32 v[40:41], v[0:1], v[40:41] op_sel_hi:[0,1]
	v_pk_mul_f32 v[48:49], v[0:1], v[48:49] op_sel_hi:[0,1]
	v_pk_mul_f32 v[56:57], v[0:1], v[56:57] op_sel_hi:[0,1]
	v_pk_mul_f32 v[60:61], v[0:1], v[60:61] op_sel_hi:[0,1]
	v_pk_mul_f32 v[36:37], v[0:1], v[36:37] op_sel_hi:[0,1]
	v_pk_mul_f32 v[44:45], v[0:1], v[44:45] op_sel_hi:[0,1]
	v_pk_mul_f32 v[52:53], v[0:1], v[52:53] op_sel_hi:[0,1]
	v_pk_mul_f32 v[32:33], v[0:1], v[32:33] op_sel_hi:[0,1]
	v_pk_mul_f32 v[38:39], v[0:1], v[38:39] op_sel_hi:[0,1]
	v_pk_mul_f32 v[46:47], v[0:1], v[46:47] op_sel_hi:[0,1]
	v_pk_mul_f32 v[54:55], v[0:1], v[54:55] op_sel_hi:[0,1]
	v_pk_mul_f32 v[58:59], v[0:1], v[58:59] op_sel_hi:[0,1]
	v_pk_mul_f32 v[34:35], v[0:1], v[34:35] op_sel_hi:[0,1]
	v_pk_mul_f32 v[42:43], v[0:1], v[42:43] op_sel_hi:[0,1]
	v_pk_mul_f32 v[50:51], v[0:1], v[50:51] op_sel_hi:[0,1]
	v_pk_mul_f32 v[30:31], v[0:1], v[30:31] op_sel_hi:[0,1]
	v_pk_mul_f32 v[4:5], v[0:1], v[4:5] op_sel_hi:[0,1]
	v_pk_mul_f32 v[2:3], v[0:1], v[2:3] op_sel_hi:[0,1]
